# nt hint also on the post-projection phases' raw-row reads
# speedup vs baseline: 1.0129x; 1.0047x over previous
.LBB0_262:
	s_cmpk_gt_i32 s0, 0x27ff
	s_mov_b64 s[14:15], -1
	s_cbranch_scc0 .LBB0_284
	s_add_i32 s14, s0, 0xffffd800
	s_and_b32 s1, s28, 0x3ff8
	s_cmpk_lt_u32 s14, 0x1000
	s_movk_i32 s14, 0xf8
	s_cselect_b32 s15, s14, 0x3f8
	s_movk_i32 s14, 0x400
	s_cselect_b32 s14, 0x100, s14
	s_and_b32 s15, s15, s28
	s_mul_i32 s46, s1, 0x2800
	s_add_i32 s26, s15, -1
	v_lshl_add_u64 v[6:7], v[86:87], 0, s[46:47]
	v_mov_b32_e32 v22, 0
	s_cmp_ge_u32 s26, s14
	v_mov_b32_e32 v26, 0
	v_mov_b32_e32 v27, 0
	v_mov_b32_e32 v28, 0
	v_mov_b32_e32 v29, 0
	s_cbranch_scc1 .LBB0_265
	v_add_co_u32_e32 v2, vcc, 0xffffe000, v6
	s_nop 1
	v_addc_co_u32_e32 v3, vcc, -1, v7, vcc
	global_load_dwordx4 v[26:29], v[2:3], off offset:-2048 nt
.LBB0_265:
	s_cmp_ge_u32 s15, s14
	v_mov_b32_e32 v23, 0
	v_mov_b32_e32 v24, 0
	v_mov_b32_e32 v25, 0
	s_cbranch_scc1 .LBB0_267
	global_load_dwordx4 v[22:25], v[6:7], off nt
.LBB0_267:
	s_or_b32 s26, s15, 1
	v_mov_b32_e32 v34, 0
	s_cmp_ge_u32 s26, s14
	v_mov_b32_e32 v30, 0
	v_mov_b32_e32 v31, 0
	v_mov_b32_e32 v32, 0
	v_mov_b32_e32 v33, 0
	s_cbranch_scc1 .LBB0_269
	v_add_co_u32_e32 v2, vcc, 0x2000, v6
	s_nop 1
	v_addc_co_u32_e32 v3, vcc, 0, v7, vcc
	global_load_dwordx4 v[30:33], v[2:3], off offset:2048 nt
.LBB0_269:
	s_or_b32 s26, s15, 2
	s_cmp_ge_u32 s26, s14
	v_mov_b32_e32 v35, 0
	v_mov_b32_e32 v36, 0
	v_mov_b32_e32 v37, 0
	s_cbranch_scc1 .LBB0_271
	v_add_co_u32_e32 v2, vcc, 0x5000, v6
	s_nop 1
	v_addc_co_u32_e32 v3, vcc, 0, v7, vcc
	global_load_dwordx4 v[34:37], v[2:3], off nt
.LBB0_271:
	s_or_b32 s26, s15, 3
	v_mov_b32_e32 v42, 0
	s_cmp_ge_u32 s26, s14
	v_mov_b32_e32 v38, 0
	v_mov_b32_e32 v39, 0
	v_mov_b32_e32 v40, 0
	v_mov_b32_e32 v41, 0
	s_cbranch_scc1 .LBB0_273
	v_add_co_u32_e32 v2, vcc, 0x7000, v6
	s_nop 1
	v_addc_co_u32_e32 v3, vcc, 0, v7, vcc
	global_load_dwordx4 v[38:41], v[2:3], off offset:2048 nt
.LBB0_273:
	s_or_b32 s26, s15, 4
	s_cmp_ge_u32 s26, s14
	v_mov_b32_e32 v43, 0
	v_mov_b32_e32 v44, 0
	v_mov_b32_e32 v45, 0
	s_cbranch_scc1 .LBB0_275
	v_add_co_u32_e32 v2, vcc, 0xa000, v6
	s_nop 1
	v_addc_co_u32_e32 v3, vcc, 0, v7, vcc
	global_load_dwordx4 v[42:45], v[2:3], off nt
.LBB0_275:
	s_or_b32 s26, s15, 5
	v_mov_b32_e32 v50, 0
	s_cmp_ge_u32 s26, s14
	v_mov_b32_e32 v46, 0
	v_mov_b32_e32 v47, 0
	v_mov_b32_e32 v48, 0
	v_mov_b32_e32 v49, 0
	s_cbranch_scc1 .LBB0_277
	v_add_co_u32_e32 v2, vcc, 0xc000, v6
	s_nop 1
	v_addc_co_u32_e32 v3, vcc, 0, v7, vcc
	global_load_dwordx4 v[46:49], v[2:3], off offset:2048 nt
.LBB0_277:
	s_or_b32 s26, s15, 6
	s_cmp_ge_u32 s26, s14
	v_mov_b32_e32 v51, 0
	v_mov_b32_e32 v52, 0
	v_mov_b32_e32 v53, 0
	s_cbranch_scc1 .LBB0_279
	v_add_co_u32_e32 v2, vcc, 0xf000, v6
	s_nop 1
	v_addc_co_u32_e32 v3, vcc, 0, v7, vcc
	global_load_dwordx4 v[50:53], v[2:3], off nt
.LBB0_279:
	s_or_b32 s26, s15, 7
	v_mov_b32_e32 v2, 0
	s_cmp_ge_u32 s26, s14
	v_mov_b32_e32 v54, 0
	v_mov_b32_e32 v55, 0
	v_mov_b32_e32 v56, 0
	v_mov_b32_e32 v57, 0
	s_cbranch_scc1 .LBB0_281
	v_add_co_u32_e32 v4, vcc, 0x11000, v6
	s_nop 1
	v_addc_co_u32_e32 v5, vcc, 0, v7, vcc
	global_load_dwordx4 v[54:57], v[4:5], off offset:2048 nt
.LBB0_281:
	s_add_i32 s15, s15, 8
	s_cmp_ge_u32 s15, s14
	v_mov_b32_e32 v3, 0
	v_mov_b32_e32 v4, 0
	v_mov_b32_e32 v5, 0
	s_cbranch_scc1 .LBB0_283
	v_add_co_u32_e32 v2, vcc, 0x14000, v6
	s_nop 1
	v_addc_co_u32_e32 v3, vcc, 0, v7, vcc
	global_load_dwordx4 v[2:5], v[2:3], off nt

.LBB0_653:
	v_add_co_u32_e32 v14, vcc, 0xfffff000, v50
	s_add_i32 s2, s16, 0xffffe000
	s_nop 0
	v_addc_co_u32_e32 v15, vcc, -1, v51, vcc
	global_load_dwordx4 v[18:21], v[14:15], off offset:-2048 nt
	global_load_dwordx4 v[10:13], v[50:51], off offset:-4096 nt
	global_load_dwordx4 v[6:9], v[50:51], off offset:-3072 nt
	global_load_dwordx4 v[2:5], v[50:51], off nt
	s_nop 0
	global_load_dwordx4 v[14:17], v[14:15], off offset:-1024 nt
	s_ashr_i32 s14, s16, 8
	s_lshr_b32 s15, s2, 10
	s_cmpk_lt_i32 s16, 0x2000
	s_cselect_b64 s[26:27], -1, 0
	s_and_b64 s[2:3], s[26:27], exec
	s_movk_i32 s2, 0x3ff
	s_cselect_b32 s2, 0xff, s2
	s_cselect_b32 s3, s14, s15
	s_and_b32 s29, s2, s16
	s_mul_i32 s2, s3, 0x500
	s_cmpk_gt_i32 s16, 0x1fff
	s_cselect_b64 s[20:21], -1, 0
	s_add_i32 s14, s29, s2
	s_lshl_b32 s3, s3, 1
	v_readlane_b32 s22, v254, 54
	s_addk_i32 s14, 0x100
	v_readlane_b32 s23, v254, 55
	s_add_i32 s2, s3, s22
	s_ashr_i32 s15, s14, 31
	s_lshl_b32 s46, s29, 8
	s_ashr_i32 s3, s2, 31
	s_lshl_b64 s[22:23], s[14:15], 11
	s_add_u32 s24, s17, s22
	s_mov_b64 s[12:13], -1
	v_lshl_add_u64 v[56:57], v[28:29], 0, s[46:47]
	s_addc_u32 s25, s18, s23
	s_and_b64 vcc, exec, s[20:21]
	s_waitcnt vmcnt(0)
	v_lshlrev_b32_e32 v22, 16, v18
	v_and_b32_e32 v23, 0xffff0000, v18
	v_lshlrev_b32_e32 v24, 16, v19
	v_and_b32_e32 v25, 0xffff0000, v19
	v_lshlrev_b32_e32 v18, 16, v20
	v_and_b32_e32 v19, 0xffff0000, v20
	v_lshlrev_b32_e32 v20, 16, v21
	v_and_b32_e32 v21, 0xffff0000, v21
	s_cbranch_vccnz .LBB0_655
	s_lshl_b64 s[12:13], s[2:3], 20
	v_lshl_add_u64 v[52:53], v[56:57], 0, v[30:31]
	v_lshl_add_u64 v[52:53], v[52:53], 0, s[12:13]
	v_lshl_add_u64 v[52:53], v[52:53], 0, v[32:33]
	s_mov_b64 s[12:13], 0
	global_store_dwordx4 v[52:53], v[22:25], off
	global_store_dwordx4 v[52:53], v[18:21], off offset:16
